# GLA scan steps 2-6: the two b128 staging writes for the next step hoisted above the tail pk_mul/MFMA group (lgkmcnt counts +2 in between)
# speedup vs baseline: 1.0052x; 1.0052x over previous
; DI void gla_scan_item(const P& p, int seq, unsigned char* smem) {
;     ...
;     auto loadr = [&](GlaRegs& R, int c) {
;         if (c >= 72) return;
;         { const int pos = tid >> 4, ch = tid & 15; R.rv = *(const u32x4*)(S + (size_t)prow(b, dir, 32 * c + pos) * NP + C_GLA_V + 128 * h + 8 * ch); }
;         { const int t2 = tid & 255, pos = t2 >> 3, ch = t2 & 7; const bf16_t* src = (tid < 256 ? QT : KO) + ((size_t)seq * PT + 32 * c + pos) * 64 + 8 * ch; R.rq = __builtin_nontemporal_load((const u32x4*)src); }
;         if (tid < 128) { const int i = tid >> 2, ch = tid & 3; R.ra = __builtin_nontemporal_load((const u32x4*)(AT + (((size_t)seq * 72 + c) * 32 + i) * 32 + 8 * ch)); }
;     ...
;     auto compute = [&](int c) {
;         const unsigned char* base = smem + (c & 1) * BUFB;
;         const bf16_t* sat = (const bf16_t*)base; const bf16_t* sqt = (const bf16_t*)(base + 2560); const bf16_t* sko = (const bf16_t*)(base + 2560 + 4608); const bf16_t* sv = (const bf16_t*)(base + 2560 + 9216); const float* sdc = (const float*)(base + 2560 + 9216 + 8704);
;         const int dv0 = 16 * w;
;         const bf16x8 vb = tr2(sv + (8 * g + q4) * 136 + dv0 + 4 * p4, sv + (8 * g + 4 + q4) * 136 + dv0 + 4 * p4);
;         bf16x8 bs[2];
;         bs[0] = packacc(st[0], st[1]); bs[1] = packacc(st[2], st[3]);
; #pragma unroll
;         for (int mt = 0; mt < 2; ++mt) {
;             f32x4 acc = (f32x4){0.f, 0.f, 0.f, 0.f};
;             acc = mfma16(vb, ld8(sat + (16 * mt + l15) * 40 + 8 * g), acc);
; #pragma unroll
;             for (int ks = 0; ks < 2; ++ks) {
;                 const bf16_t* r0 = sqt + (16 * mt + l15) * 72 + 32 * ks + 4 * g;
;                 acc = mfma16(bs[ks], ld4x2(r0, r0 + 16), acc);
;             }
;             bf16_t* ob = OG + (size_t)prow(b, dir, 32 * c) * 512 + 128 * h;
;             u32x2 ov; ov.x = pk2(acc[0], acc[1]); ov.y = pk2(acc[2], acc[3]);
;             *(u32x2*)(ob + sgn * ((16 * mt + l15) * 512) + dv0 + 4 * g) = ov;
;         }
; #pragma unroll
;         for (int dt = 0; dt < 4; ++dt) {
;             const bf16x8 ak = tr2(sko + (8 * g + q4) * 72 + 16 * dt + 4 * p4, sko + (8 * g + 4 + q4) * 72 + 16 * dt + 4 * p4);
; #pragma unroll
;             for (int r = 0; r < 4; ++r) st[dt][r] *= sdc[16 * dt + 4 * g + r];
;             st[dt] = mfma16(ak, vb, st[dt]);
;         }
;     };
.LBB0_590:
	v_cvt_pk_bf16_f32 v96, v84, v85
	v_cvt_pk_bf16_f32 v99, v78, v79
	v_add_u32_e32 v152, 0x800, v126
	ds_read2_b64 v[208:211], v152 offset0:64 offset1:68
	ds_read2_b64 v[212:215], v152 offset0:72 offset1:76
	v_cvt_pk_bf16_f32 v98, v76, v77
	v_cvt_pk_bf16_f32 v97, v86, v87
	s_sub_i32 s4, s26, 64
	s_add_i32 s5, s26, 0xfffffec0
	s_add_i32 s6, s27, 0xa0
	s_add_i32 s7, s27, 0xfffff8a0
	s_waitcnt lgkmcnt(9)
	v_mfma_f32_16x16x32_bf16 v[92:95], v[200:203], v[204:207], 0
	s_and_b64 s[2:3], s[0:1], exec
	s_cselect_b32 s2, s4, s7
	s_add_i32 s4, s2, s22
	s_and_b64 s[2:3], s[0:1], exec
	s_waitcnt lgkmcnt(1)
	v_mfma_f32_16x16x32_bf16 v[92:95], v[96:99], v[208:211], v[92:95]
	ds_read_b64_tr_b16 v[208:209], v143 offset:7264
	ds_read_b64_tr_b16 v[210:211], v144 offset:7264
	v_cvt_pk_bf16_f32 v156, v72, v73
	v_cvt_pk_bf16_f32 v155, v82, v83
	v_cvt_pk_bf16_f32 v154, v80, v81
	v_cvt_pk_bf16_f32 v157, v74, v75
	s_cselect_b32 s2, s5, s6
	s_add_i32 s5, s2, s21
	s_cmp_lt_u32 s24, 8
	s_cselect_b64 s[36:37], -1, 0
	s_waitcnt lgkmcnt(2)
	v_mfma_f32_16x16x32_bf16 v[92:95], v[154:157], v[212:215], v[92:95]
	s_and_b64 s[2:3], s[36:37], exec
	s_cselect_b32 s2, s4, s5
	s_ashr_i32 s3, s2, 31
	s_lshl_b64 s[42:43], s[2:3], 10
	v_add_u32_e32 v151, 0x800, v142
	ds_read2_b64 v[224:227], v151 offset0:64 offset1:68
	ds_read2_b64 v[228:231], v151 offset0:72 offset1:76
	s_nop 2
	v_cvt_pk_bf16_f32 v92, v92, v93
	v_cvt_pk_bf16_f32 v93, v94, v95
	v_lshl_add_u64 v[94:95], v[100:101], 0, s[42:43]
	global_store_dwordx2 v[94:95], v[92:93], off
	v_mfma_f32_16x16x32_bf16 v[92:95], v[200:203], v[216:219], 0
	v_add_u32_e32 v153, 0x5000, v145
	ds_read2_b32 v[232:233], v153 offset1:1
	s_waitcnt lgkmcnt(2)
	v_mfma_f32_16x16x32_bf16 v[92:95], v[96:99], v[224:227], v[92:95]
	v_add_u32_e32 v158, 0x5040, v145
	ds_read2_b32 v[244:245], v158 offset1:1
	v_add_u32_e32 v161, 0x50c0, v145
	ds_read2_b32 v[212:213], v161 offset1:1
	s_waitcnt lgkmcnt(3)
	v_mfma_f32_16x16x32_bf16 v[92:95], v[154:157], v[228:231], v[92:95]
	v_add_u32_e32 v156, 0x5008, v145
	ds_read2_b32 v[234:235], v156 offset1:1
	v_add_u32_e32 v157, 0x5048, v145
	ds_read2_b32 v[246:247], v157 offset1:1
	v_add_u32_e32 v154, 0x5080, v145
	ds_read2_b32 v[204:205], v154 offset1:1
	s_nop 4
	v_cvt_pk_bf16_f32 v92, v92, v93
	v_cvt_pk_bf16_f32 v93, v94, v95
	v_lshl_add_u64 v[94:95], v[102:103], 0, s[42:43]
	global_store_dwordx2 v[94:95], v[92:93], off
	v_add_u32_e32 v155, 0x5088, v145
	ds_read2_b32 v[206:207], v155 offset1:1
	v_add_u32_e32 v160, 0x50c8, v145
	ds_read2_b32 v[214:215], v160 offset1:1
	s_waitcnt vmcnt(11)
	ds_write_b128 v121, v[12:15] offset:32512
	s_waitcnt vmcnt(10)
	ds_write_b128 v122, v[20:23] offset:20736
	s_waitcnt lgkmcnt(9)
	v_pk_mul_f32 v[84:85], v[84:85], v[232:233]
	s_waitcnt lgkmcnt(6)
	v_pk_mul_f32 v[86:87], v[86:87], v[234:235]
	s_nop 1
	v_mfma_f32_16x16x32_bf16 v[84:87], v[236:239], v[200:203], v[84:87]
	v_pk_mul_f32 v[76:77], v[76:77], v[244:245]
	s_waitcnt lgkmcnt(5)
	v_pk_mul_f32 v[78:79], v[78:79], v[246:247]
	s_nop 1
	v_mfma_f32_16x16x32_bf16 v[76:79], v[240:243], v[200:203], v[76:79]
	s_waitcnt lgkmcnt(4)
	v_pk_mul_f32 v[80:81], v[80:81], v[204:205]
	s_waitcnt lgkmcnt(3)
	v_pk_mul_f32 v[82:83], v[82:83], v[206:207]
	s_nop 1
	v_mfma_f32_16x16x32_bf16 v[80:83], v[248:251], v[200:203], v[80:83]
	v_pk_mul_f32 v[72:73], v[72:73], v[212:213]
	s_waitcnt lgkmcnt(2)
	v_pk_mul_f32 v[74:75], v[74:75], v[214:215]
	s_nop 1
	v_mfma_f32_16x16x32_bf16 v[72:75], v[208:211], v[200:203], v[72:75]
	s_and_saveexec_b64 s[42:43], s[38:39]
	ds_write_b128 v148, v[16:19] offset:20736
	s_or_b64 exec, exec, s[42:43]
	s_and_saveexec_b64 s[42:43], s[40:41]
	ds_write_b32 v149, v116 offset:40704
	s_or_b64 exec, exec, s[42:43]
	s_cmp_gt_u32 s24, 64
	s_waitcnt lgkmcnt(0)
	s_barrier
	ds_read_b64_tr_b16 v[200:201], v123 offset:32512
	ds_read_b64_tr_b16 v[202:203], v124 offset:32512
	ds_read_b128 v[204:207], v125 offset:20736
	ds_read_b128 v[216:219], v127 offset:20736
	ds_read_b64_tr_b16 v[238:239], v147 offset:27904
	ds_read_b64_tr_b16 v[242:243], v147 offset:27936
	ds_read_b64_tr_b16 v[236:237], v146 offset:27904
	ds_read_b64_tr_b16 v[240:241], v146 offset:27936
	ds_read_b64_tr_b16 v[248:249], v146 offset:27968
	ds_read_b64_tr_b16 v[250:251], v147 offset:27968
	s_cbranch_scc1 .LBB0_600
	v_add_u32_e32 v12, 0xa0, v150
	s_movk_i32 s2, 0x100
	v_cmp_gt_i32_e32 vcc, s2, v12
	v_add_u32_e32 v13, 0xffffffa0, v150
	v_mov_b32_e32 v15, s22
	v_cndmask_b32_e32 v14, v174, v175, vcc
	v_add3_u32 v14, v132, v14, s27
	v_cndmask_b32_e32 v12, v13, v12, vcc
	v_mov_b32_e32 v13, s21
	v_add_u32_e32 v14, 0xfffff6c1, v14
	v_cndmask_b32_e32 v13, v13, v15, vcc
	v_cndmask_b32_e64 v12, v14, v12, s[0:1]
	v_add_u32_e32 v12, v12, v13
	s_movk_i32 s2, 0x3800
	v_add_co_u32_e32 v20, vcc, 0x7000, v112
	v_mad_i64_i32 v[12:13], s[2:3], v12, s2, v[104:105]
	s_nop 0
	v_addc_co_u32_e32 v21, vcc, 0, v113, vcc
	global_load_dwordx4 v[12:15], v[12:13], off offset:1024
	s_nop 0
	global_load_dwordx4 v[20:23], v[20:21], off nt
	s_and_saveexec_b64 s[42:43], s[38:39]
	s_cbranch_execz .LBB0_597
	v_lshl_add_u64 v[16:17], v[106:107], 0, s[44:45]
	v_add_co_u32_e32 v16, vcc, 0x1283f000, v16
	s_nop 1
	v_addc_co_u32_e32 v17, vcc, 0, v17, vcc
	global_load_dwordx4 v[16:19], v[16:17], off offset:2048 nt

; DI void gla_scan_item(const P& p, int seq, unsigned char* smem) {
;     ...
;     auto loadr = [&](GlaRegs& R, int c) {
;         if (c >= 72) return;
;         { const int pos = tid >> 4, ch = tid & 15; R.rv = *(const u32x4*)(S + (size_t)prow(b, dir, 32 * c + pos) * NP + C_GLA_V + 128 * h + 8 * ch); }
;         { const int t2 = tid & 255, pos = t2 >> 3, ch = t2 & 7; const bf16_t* src = (tid < 256 ? QT : KO) + ((size_t)seq * PT + 32 * c + pos) * 64 + 8 * ch; R.rq = __builtin_nontemporal_load((const u32x4*)src); }
;         if (tid < 128) { const int i = tid >> 2, ch = tid & 3; R.ra = __builtin_nontemporal_load((const u32x4*)(AT + (((size_t)seq * 72 + c) * 32 + i) * 32 + 8 * ch)); }
;     ...
;     auto compute = [&](int c) {
;         const unsigned char* base = smem + (c & 1) * BUFB;
;         const bf16_t* sat = (const bf16_t*)base; const bf16_t* sqt = (const bf16_t*)(base + 2560); const bf16_t* sko = (const bf16_t*)(base + 2560 + 4608); const bf16_t* sv = (const bf16_t*)(base + 2560 + 9216); const float* sdc = (const float*)(base + 2560 + 9216 + 8704);
;         const int dv0 = 16 * w;
;         const bf16x8 vb = tr2(sv + (8 * g + q4) * 136 + dv0 + 4 * p4, sv + (8 * g + 4 + q4) * 136 + dv0 + 4 * p4);
;         bf16x8 bs[2];
;         bs[0] = packacc(st[0], st[1]); bs[1] = packacc(st[2], st[3]);
; #pragma unroll
;         for (int mt = 0; mt < 2; ++mt) {
;             f32x4 acc = (f32x4){0.f, 0.f, 0.f, 0.f};
;             acc = mfma16(vb, ld8(sat + (16 * mt + l15) * 40 + 8 * g), acc);
; #pragma unroll
;             for (int ks = 0; ks < 2; ++ks) {
;                 const bf16_t* r0 = sqt + (16 * mt + l15) * 72 + 32 * ks + 4 * g;
;                 acc = mfma16(bs[ks], ld4x2(r0, r0 + 16), acc);
;             }
;             bf16_t* ob = OG + (size_t)prow(b, dir, 32 * c) * 512 + 128 * h;
;             u32x2 ov; ov.x = pk2(acc[0], acc[1]); ov.y = pk2(acc[2], acc[3]);
;             *(u32x2*)(ob + sgn * ((16 * mt + l15) * 512) + dv0 + 4 * g) = ov;
;         }
; #pragma unroll
;         for (int dt = 0; dt < 4; ++dt) {
;             const bf16x8 ak = tr2(sko + (8 * g + q4) * 72 + 16 * dt + 4 * p4, sko + (8 * g + 4 + q4) * 72 + 16 * dt + 4 * p4);
; #pragma unroll
;             for (int r = 0; r < 4; ++r) st[dt][r] *= sdc[16 * dt + 4 * g + r];
;             st[dt] = mfma16(ak, vb, st[dt]);
;         }
;     };
.LBB0_600:
	v_cvt_pk_bf16_f32 v96, v84, v85
	v_cvt_pk_bf16_f32 v99, v78, v79
	v_add_u32_e32 v159, 0x5800, v126
	ds_read2_b64 v[208:211], v159 offset0:96 offset1:100
	ds_read2_b64 v[212:215], v159 offset0:104 offset1:108
	v_cvt_pk_bf16_f32 v98, v76, v77
	v_cvt_pk_bf16_f32 v97, v86, v87
	s_waitcnt lgkmcnt(9)
	v_mfma_f32_16x16x32_bf16 v[88:91], v[200:203], v[204:207], 0
	s_sub_i32 s4, s26, 32
	s_add_i32 s5, s26, 0xfffffee0
	s_add_i32 s6, s27, 0x80
	s_add_i32 s7, s27, 0xfffff880
	s_and_b64 s[2:3], s[0:1], exec
	s_waitcnt lgkmcnt(1)
	v_mfma_f32_16x16x32_bf16 v[162:165], v[96:99], v[208:211], v[88:91]
	ds_read_b64_tr_b16 v[208:209], v146 offset:28000
	ds_read_b64_tr_b16 v[210:211], v147 offset:28000
	s_cselect_b32 s2, s4, s7
	s_add_i32 s4, s2, s22
	s_and_b64 s[2:3], s[0:1], exec
	v_cvt_pk_bf16_f32 v90, v72, v73
	v_cvt_pk_bf16_f32 v89, v82, v83
	v_cvt_pk_bf16_f32 v88, v80, v81
	v_cvt_pk_bf16_f32 v91, v74, v75
	s_cselect_b32 s2, s5, s6
	s_add_i32 s5, s2, s21
	s_waitcnt lgkmcnt(2)
	v_mfma_f32_16x16x32_bf16 v[162:165], v[88:91], v[212:215], v[162:165]
	s_and_b64 s[2:3], s[36:37], exec
	s_cselect_b32 s2, s4, s5
	s_ashr_i32 s3, s2, 31
	s_lshl_b64 s[36:37], s[2:3], 10
	s_nop 3
	v_cvt_pk_bf16_f32 v134, v162, v163
	v_cvt_pk_bf16_f32 v135, v164, v165
	v_lshl_add_u64 v[162:163], v[100:101], 0, s[36:37]
	global_store_dwordx2 v[162:163], v[134:135], off
	v_mfma_f32_16x16x32_bf16 v[184:187], v[200:203], v[216:219], 0
	v_add_u32_e32 v162, 0x5800, v142
	ds_read2_b64 v[224:227], v162 offset0:96 offset1:100
	ds_read2_b64 v[228:231], v162 offset0:104 offset1:108
	v_add_u32_e32 v163, 0xa100, v145
	ds_read2_b32 v[232:233], v163 offset1:1
	s_waitcnt lgkmcnt(2)
	v_mfma_f32_16x16x32_bf16 v[96:99], v[96:99], v[224:227], v[184:187]
	s_nop 2
	v_add_u32_e32 v183, 0xa108, v145
	ds_read2_b32 v[234:235], v183 offset1:1
	v_add_u32_e32 v164, 0xa180, v145
	ds_read2_b32 v[204:205], v164 offset1:1
	s_waitcnt lgkmcnt(3)
	v_mfma_f32_16x16x32_bf16 v[88:91], v[88:91], v[228:231], v[96:99]
	v_add_u32_e32 v185, 0xa140, v145
	ds_read2_b32 v[244:245], v185 offset1:1
	v_add_u32_e32 v184, 0xa148, v145
	ds_read2_b32 v[246:247], v184 offset1:1
	v_add_u32_e32 v165, 0xa188, v145
	ds_read2_b32 v[206:207], v165 offset1:1
	s_nop 4
	v_cvt_pk_bf16_f32 v88, v88, v89
	v_cvt_pk_bf16_f32 v89, v90, v91
	v_lshl_add_u64 v[90:91], v[102:103], 0, s[36:37]
	global_store_dwordx2 v[90:91], v[88:89], off
	v_add_u32_e32 v187, 0xa1c0, v145
	ds_read2_b32 v[212:213], v187 offset1:1
	v_add_u32_e32 v186, 0xa1c8, v145
	ds_read2_b32 v[214:215], v186 offset1:1
	s_waitcnt vmcnt(11)
	ds_write_b128 v121, v[24:27] offset:11776
	s_waitcnt vmcnt(10)
	ds_write_b128 v122, v[32:35]
	s_waitcnt lgkmcnt(9)
	v_pk_mul_f32 v[84:85], v[84:85], v[232:233]
	s_waitcnt lgkmcnt(8)
	v_pk_mul_f32 v[86:87], v[86:87], v[234:235]
	s_nop 1
	v_mfma_f32_16x16x32_bf16 v[88:91], v[236:239], v[200:203], v[84:87]
	s_nop 2
	s_waitcnt lgkmcnt(6)
	v_pk_mul_f32 v[76:77], v[76:77], v[244:245]
	s_waitcnt lgkmcnt(5)
	v_pk_mul_f32 v[78:79], v[78:79], v[246:247]
	s_nop 1
	v_mfma_f32_16x16x32_bf16 v[84:87], v[240:243], v[200:203], v[76:79]
	s_nop 2
	v_pk_mul_f32 v[80:81], v[80:81], v[204:205]
	s_waitcnt lgkmcnt(4)
	v_pk_mul_f32 v[82:83], v[82:83], v[206:207]
	s_nop 1
	v_mfma_f32_16x16x32_bf16 v[76:79], v[248:251], v[200:203], v[80:83]
	s_nop 2
	s_waitcnt lgkmcnt(3)
	v_pk_mul_f32 v[72:73], v[72:73], v[212:213]
	s_waitcnt lgkmcnt(2)
	v_pk_mul_f32 v[74:75], v[74:75], v[214:215]
	s_nop 1
	v_mfma_f32_16x16x32_bf16 v[80:83], v[208:211], v[200:203], v[72:75]
	s_and_saveexec_b64 s[36:37], s[38:39]
	ds_write_b128 v148, v[28:31]
	s_or_b64 exec, exec, s[36:37]
	s_and_saveexec_b64 s[36:37], s[40:41]
	ds_write_b32 v149, v117 offset:19968
	s_or_b64 exec, exec, s[36:37]
	s_cmp_gt_u32 s24, 63
	s_waitcnt lgkmcnt(0)
	s_barrier
	ds_read_b64_tr_b16 v[200:201], v123 offset:11776
	ds_read_b64_tr_b16 v[202:203], v124 offset:11776
	ds_read_b128 v[204:207], v125
	ds_read2_b64 v[208:211], v152 offset0:64 offset1:68
	ds_read2_b64 v[212:215], v152 offset0:72 offset1:76
	ds_read2_b64 v[216:219], v151 offset0:64 offset1:68
	ds_read_b128 v[224:227], v127
	ds_read2_b64 v[228:231], v151 offset0:72 offset1:76
	ds_read2_b32 v[232:233], v153 offset1:1
	ds_read2_b32 v[234:235], v156 offset1:1
	ds_read_b64_tr_b16 v[238:239], v144 offset:7168
	ds_read_b64_tr_b16 v[242:243], v144 offset:7200
	s_cbranch_scc1 .LBB0_610
	v_add_u32_e32 v24, 0xc0, v150
	s_movk_i32 s2, 0x100
	v_cmp_gt_i32_e32 vcc, s2, v24
	v_subrev_u32_e32 v25, 64, v150
	v_mov_b32_e32 v27, s22
	v_cndmask_b32_e32 v26, v174, v175, vcc
	v_add3_u32 v26, v132, v26, s27
	v_cndmask_b32_e32 v24, v25, v24, vcc
	v_mov_b32_e32 v25, s21
	v_add_u32_e32 v26, 0xfffff6a1, v26
	v_cndmask_b32_e32 v25, v25, v27, vcc
	v_cndmask_b32_e64 v24, v26, v24, s[0:1]
	v_add_u32_e32 v24, v24, v25
	s_movk_i32 s2, 0x3800
	v_add_co_u32_e32 v32, vcc, 0x8000, v112
	v_mad_i64_i32 v[24:25], s[2:3], v24, s2, v[104:105]
	s_nop 0
	v_addc_co_u32_e32 v33, vcc, 0, v113, vcc
	global_load_dwordx4 v[24:27], v[24:25], off offset:1024
	s_nop 0
	global_load_dwordx4 v[32:35], v[32:33], off nt
	s_and_saveexec_b64 s[36:37], s[38:39]
	s_cbranch_execz .LBB0_607
	v_lshl_add_u64 v[28:29], v[106:107], 0, s[44:45]
	v_add_co_u32_e32 v28, vcc, 0x12840000, v28
	s_nop 1
	v_addc_co_u32_e32 v29, vcc, 0, v29, vcc
	global_load_dwordx4 v[28:31], v[28:29], off nt

; DI void gla_scan_item(const P& p, int seq, unsigned char* smem) {
;     ...
;     auto loadr = [&](GlaRegs& R, int c) {
;         if (c >= 72) return;
;         { const int pos = tid >> 4, ch = tid & 15; R.rv = *(const u32x4*)(S + (size_t)prow(b, dir, 32 * c + pos) * NP + C_GLA_V + 128 * h + 8 * ch); }
;         { const int t2 = tid & 255, pos = t2 >> 3, ch = t2 & 7; const bf16_t* src = (tid < 256 ? QT : KO) + ((size_t)seq * PT + 32 * c + pos) * 64 + 8 * ch; R.rq = __builtin_nontemporal_load((const u32x4*)src); }
;         if (tid < 128) { const int i = tid >> 2, ch = tid & 3; R.ra = __builtin_nontemporal_load((const u32x4*)(AT + (((size_t)seq * 72 + c) * 32 + i) * 32 + 8 * ch)); }
;     ...
;     auto compute = [&](int c) {
;         const unsigned char* base = smem + (c & 1) * BUFB;
;         const bf16_t* sat = (const bf16_t*)base; const bf16_t* sqt = (const bf16_t*)(base + 2560); const bf16_t* sko = (const bf16_t*)(base + 2560 + 4608); const bf16_t* sv = (const bf16_t*)(base + 2560 + 9216); const float* sdc = (const float*)(base + 2560 + 9216 + 8704);
;         const int dv0 = 16 * w;
;         const bf16x8 vb = tr2(sv + (8 * g + q4) * 136 + dv0 + 4 * p4, sv + (8 * g + 4 + q4) * 136 + dv0 + 4 * p4);
;         bf16x8 bs[2];
;         bs[0] = packacc(st[0], st[1]); bs[1] = packacc(st[2], st[3]);
; #pragma unroll
;         for (int mt = 0; mt < 2; ++mt) {
;             f32x4 acc = (f32x4){0.f, 0.f, 0.f, 0.f};
;             acc = mfma16(vb, ld8(sat + (16 * mt + l15) * 40 + 8 * g), acc);
; #pragma unroll
;             for (int ks = 0; ks < 2; ++ks) {
;                 const bf16_t* r0 = sqt + (16 * mt + l15) * 72 + 32 * ks + 4 * g;
;                 acc = mfma16(bs[ks], ld4x2(r0, r0 + 16), acc);
;             }
;             bf16_t* ob = OG + (size_t)prow(b, dir, 32 * c) * 512 + 128 * h;
;             u32x2 ov; ov.x = pk2(acc[0], acc[1]); ov.y = pk2(acc[2], acc[3]);
;             *(u32x2*)(ob + sgn * ((16 * mt + l15) * 512) + dv0 + 4 * g) = ov;
;         }
; #pragma unroll
;         for (int dt = 0; dt < 4; ++dt) {
;             const bf16x8 ak = tr2(sko + (8 * g + q4) * 72 + 16 * dt + 4 * p4, sko + (8 * g + 4 + q4) * 72 + 16 * dt + 4 * p4);
; #pragma unroll
;             for (int r = 0; r < 4; ++r) st[dt][r] *= sdc[16 * dt + 4 * g + r];
;             st[dt] = mfma16(ak, vb, st[dt]);
;         }
;     };
.LBB0_610:
	v_cvt_pk_bf16_f32 v98, v84, v85
	v_cvt_pk_bf16_f32 v97, v90, v91
	v_cvt_pk_bf16_f32 v96, v88, v89
	v_cvt_pk_bf16_f32 v99, v86, v87
	s_waitcnt lgkmcnt(9)
	v_mfma_f32_16x16x32_bf16 v[72:75], v[200:203], v[204:207], 0
	ds_read_b64_tr_b16 v[236:237], v143 offset:7168
	ds_read_b64_tr_b16 v[240:241], v143 offset:7200
	ds_read2_b32 v[244:245], v158 offset1:1
	s_add_i32 s4, s26, 0xffffff00
	s_add_i32 s5, s27, 0x60
	s_add_i32 s6, s27, 0xfffff860
	s_and_b64 s[2:3], s[0:1], exec
	s_cselect_b32 s2, s26, s6
	s_waitcnt lgkmcnt(11)
	v_mfma_f32_16x16x32_bf16 v[72:75], v[96:99], v[208:211], v[72:75]
	ds_read2_b32 v[246:247], v157 offset1:1
	v_cvt_pk_bf16_f32 v190, v80, v81
	v_cvt_pk_bf16_f32 v189, v78, v79
	v_cvt_pk_bf16_f32 v188, v76, v77
	v_cvt_pk_bf16_f32 v191, v82, v83
	s_add_i32 s6, s2, s22
	s_and_b64 s[2:3], s[0:1], exec
	s_cselect_b32 s2, s4, s5
	s_add_i32 s2, s2, s21
	s_cmp_lt_u32 s24, 6
	s_waitcnt lgkmcnt(11)
	v_mfma_f32_16x16x32_bf16 v[72:75], v[188:191], v[212:215], v[72:75]
	ds_read_b64_tr_b16 v[248:249], v143 offset:7232
	s_cselect_b32 s2, s6, s2
	s_ashr_i32 s3, s2, 31
	s_lshl_b64 s[36:37], s[2:3], 10
	s_nop 3
	v_cvt_pk_bf16_f32 v72, v72, v73
	v_cvt_pk_bf16_f32 v73, v74, v75
	v_lshl_add_u64 v[74:75], v[100:101], 0, s[36:37]
	global_store_dwordx2 v[74:75], v[72:73], off
	s_waitcnt lgkmcnt(10)
	v_mfma_f32_16x16x32_bf16 v[72:75], v[200:203], v[224:227], 0
	ds_read_b64_tr_b16 v[250:251], v144 offset:7232
	ds_read2_b32 v[204:205], v154 offset1:1
	v_mfma_f32_16x16x32_bf16 v[72:75], v[96:99], v[216:219], v[72:75]
	s_waitcnt lgkmcnt(11)
	v_mfma_f32_16x16x32_bf16 v[72:75], v[188:191], v[228:231], v[72:75]
	ds_read2_b32 v[206:207], v155 offset1:1
	s_nop 7
	v_cvt_pk_bf16_f32 v72, v72, v73
	v_cvt_pk_bf16_f32 v73, v74, v75
	v_lshl_add_u64 v[74:75], v[102:103], 0, s[36:37]
	global_store_dwordx2 v[74:75], v[72:73], off
	s_waitcnt lgkmcnt(11)
	v_pk_mul_f32 v[72:73], v[88:89], v[232:233]
	ds_read_b64_tr_b16 v[208:209], v143 offset:7264
	s_waitcnt lgkmcnt(11)
	v_pk_mul_f32 v[74:75], v[90:91], v[234:235]
	ds_read_b64_tr_b16 v[210:211], v144 offset:7264
	s_waitcnt lgkmcnt(9)
	v_mfma_f32_16x16x32_bf16 v[88:91], v[236:239], v[200:203], v[72:75]
	ds_read2_b32 v[212:213], v161 offset1:1
	ds_read2_b32 v[214:215], v160 offset1:1
	s_waitcnt vmcnt(11)
	ds_write_b128 v121, v[36:39] offset:32512
	s_waitcnt vmcnt(10)
	ds_write_b128 v122, v[44:47] offset:20736
	s_nop 2
	s_waitcnt lgkmcnt(11)
	v_pk_mul_f32 v[72:73], v[84:85], v[244:245]
	s_waitcnt lgkmcnt(10)
	v_pk_mul_f32 v[74:75], v[86:87], v[246:247]
	s_nop 1
	v_mfma_f32_16x16x32_bf16 v[72:75], v[240:243], v[200:203], v[72:75]
	s_waitcnt lgkmcnt(7)
	v_pk_mul_f32 v[76:77], v[76:77], v[204:205]
	s_waitcnt lgkmcnt(6)
	v_pk_mul_f32 v[78:79], v[78:79], v[206:207]
	s_nop 1
	v_mfma_f32_16x16x32_bf16 v[76:79], v[248:251], v[200:203], v[76:79]
	s_waitcnt lgkmcnt(3)
	v_pk_mul_f32 v[80:81], v[80:81], v[212:213]
	s_waitcnt lgkmcnt(2)
	v_pk_mul_f32 v[82:83], v[82:83], v[214:215]
	s_nop 1
	v_mfma_f32_16x16x32_bf16 v[80:83], v[208:211], v[200:203], v[80:83]
	s_and_saveexec_b64 s[36:37], s[38:39]
	ds_write_b128 v148, v[40:43] offset:20736
	s_or_b64 exec, exec, s[36:37]
	s_and_saveexec_b64 s[36:37], s[40:41]
	ds_write_b32 v149, v118 offset:40704
	s_or_b64 exec, exec, s[36:37]
	s_cmp_gt_u32 s24, 62
	s_waitcnt lgkmcnt(0)
	s_barrier
	ds_read_b64_tr_b16 v[200:201], v123 offset:32512
	ds_read_b64_tr_b16 v[202:203], v124 offset:32512
	ds_read_b128 v[204:207], v125 offset:20736
	ds_read2_b64 v[208:211], v159 offset0:96 offset1:100
	ds_read2_b64 v[212:215], v159 offset0:104 offset1:108
	ds_read2_b64 v[216:219], v162 offset0:96 offset1:100
	ds_read_b128 v[224:227], v127 offset:20736
	ds_read2_b64 v[228:231], v162 offset0:104 offset1:108
	ds_read2_b32 v[232:233], v163 offset1:1
	ds_read2_b32 v[234:235], v183 offset1:1
	ds_read_b64_tr_b16 v[238:239], v147 offset:27904
	ds_read_b64_tr_b16 v[242:243], v147 offset:27936
	s_cbranch_scc1 .LBB0_620
	v_add_u32_e32 v36, 0xe0, v150
	s_movk_i32 s2, 0x100
	v_cmp_gt_i32_e32 vcc, s2, v36
	v_subrev_u32_e32 v37, 32, v150
	v_mov_b32_e32 v39, s22
	v_cndmask_b32_e32 v38, v174, v175, vcc
	v_add3_u32 v38, v132, v38, s27
	v_cndmask_b32_e32 v36, v37, v36, vcc
	v_mov_b32_e32 v37, s21
	v_add_u32_e32 v38, 0xfffff681, v38
	v_cndmask_b32_e32 v37, v37, v39, vcc
	v_cndmask_b32_e64 v36, v38, v36, s[0:1]
	v_add_u32_e32 v36, v36, v37
	s_movk_i32 s2, 0x3800
	v_add_co_u32_e32 v44, vcc, 0x9000, v112
	v_mad_i64_i32 v[36:37], s[2:3], v36, s2, v[104:105]
	s_nop 0
	v_addc_co_u32_e32 v45, vcc, 0, v113, vcc
	global_load_dwordx4 v[36:39], v[36:37], off offset:1024
	s_nop 0
	global_load_dwordx4 v[44:47], v[44:45], off nt
	s_and_saveexec_b64 s[36:37], s[38:39]
	s_cbranch_execz .LBB0_617
	v_lshl_add_u64 v[40:41], v[106:107], 0, s[44:45]
	v_add_co_u32_e32 v40, vcc, 0x12840000, v40
	s_nop 1
	v_addc_co_u32_e32 v41, vcc, 0, v41, vcc
	global_load_dwordx4 v[40:43], v[40:41], off offset:2048 nt

; DI void gla_scan_item(const P& p, int seq, unsigned char* smem) {
;     ...
;     auto loadr = [&](GlaRegs& R, int c) {
;         if (c >= 72) return;
;         { const int pos = tid >> 4, ch = tid & 15; R.rv = *(const u32x4*)(S + (size_t)prow(b, dir, 32 * c + pos) * NP + C_GLA_V + 128 * h + 8 * ch); }
;         { const int t2 = tid & 255, pos = t2 >> 3, ch = t2 & 7; const bf16_t* src = (tid < 256 ? QT : KO) + ((size_t)seq * PT + 32 * c + pos) * 64 + 8 * ch; R.rq = __builtin_nontemporal_load((const u32x4*)src); }
;         if (tid < 128) { const int i = tid >> 2, ch = tid & 3; R.ra = __builtin_nontemporal_load((const u32x4*)(AT + (((size_t)seq * 72 + c) * 32 + i) * 32 + 8 * ch)); }
;     ...
;     auto compute = [&](int c) {
;         const unsigned char* base = smem + (c & 1) * BUFB;
;         const bf16_t* sat = (const bf16_t*)base; const bf16_t* sqt = (const bf16_t*)(base + 2560); const bf16_t* sko = (const bf16_t*)(base + 2560 + 4608); const bf16_t* sv = (const bf16_t*)(base + 2560 + 9216); const float* sdc = (const float*)(base + 2560 + 9216 + 8704);
;         const int dv0 = 16 * w;
;         const bf16x8 vb = tr2(sv + (8 * g + q4) * 136 + dv0 + 4 * p4, sv + (8 * g + 4 + q4) * 136 + dv0 + 4 * p4);
;         bf16x8 bs[2];
;         bs[0] = packacc(st[0], st[1]); bs[1] = packacc(st[2], st[3]);
; #pragma unroll
;         for (int mt = 0; mt < 2; ++mt) {
;             f32x4 acc = (f32x4){0.f, 0.f, 0.f, 0.f};
;             acc = mfma16(vb, ld8(sat + (16 * mt + l15) * 40 + 8 * g), acc);
; #pragma unroll
;             for (int ks = 0; ks < 2; ++ks) {
;                 const bf16_t* r0 = sqt + (16 * mt + l15) * 72 + 32 * ks + 4 * g;
;                 acc = mfma16(bs[ks], ld4x2(r0, r0 + 16), acc);
;             }
;             bf16_t* ob = OG + (size_t)prow(b, dir, 32 * c) * 512 + 128 * h;
;             u32x2 ov; ov.x = pk2(acc[0], acc[1]); ov.y = pk2(acc[2], acc[3]);
;             *(u32x2*)(ob + sgn * ((16 * mt + l15) * 512) + dv0 + 4 * g) = ov;
;         }
; #pragma unroll
;         for (int dt = 0; dt < 4; ++dt) {
;             const bf16x8 ak = tr2(sko + (8 * g + q4) * 72 + 16 * dt + 4 * p4, sko + (8 * g + 4 + q4) * 72 + 16 * dt + 4 * p4);
; #pragma unroll
;             for (int r = 0; r < 4; ++r) st[dt][r] *= sdc[16 * dt + 4 * g + r];
;             st[dt] = mfma16(ak, vb, st[dt]);
;         }
;     };
.LBB0_620:
	v_cvt_pk_bf16_f32 v98, v72, v73
	v_cvt_pk_bf16_f32 v97, v90, v91
	v_cvt_pk_bf16_f32 v96, v88, v89
	v_cvt_pk_bf16_f32 v99, v74, v75
	s_waitcnt lgkmcnt(9)
	v_mfma_f32_16x16x32_bf16 v[92:95], v[200:203], v[204:207], 0
	ds_read_b64_tr_b16 v[236:237], v146 offset:27904
	ds_read_b64_tr_b16 v[240:241], v146 offset:27936
	ds_read2_b32 v[244:245], v185 offset1:1
	s_add_i32 s4, s26, 32
	s_add_i32 s5, s26, 0xffffff20
	s_add_i32 s6, s27, 64
	s_add_i32 s7, s27, 0xfffff840
	s_and_b64 s[2:3], s[0:1], exec
	s_cselect_b32 s2, s4, s7
	s_waitcnt lgkmcnt(11)
	v_mfma_f32_16x16x32_bf16 v[92:95], v[96:99], v[208:211], v[92:95]
	ds_read2_b32 v[246:247], v184 offset1:1
	v_cvt_pk_bf16_f32 v190, v80, v81
	v_cvt_pk_bf16_f32 v189, v78, v79
	v_cvt_pk_bf16_f32 v188, v76, v77
	v_cvt_pk_bf16_f32 v191, v82, v83
	s_add_i32 s4, s2, s22
	s_and_b64 s[2:3], s[0:1], exec
	s_cselect_b32 s2, s5, s6
	s_add_i32 s2, s2, s21
	s_cmp_lt_u32 s24, 5
	s_waitcnt lgkmcnt(11)
	v_mfma_f32_16x16x32_bf16 v[92:95], v[188:191], v[212:215], v[92:95]
	ds_read_b64_tr_b16 v[248:249], v146 offset:27968
	s_cselect_b32 s2, s4, s2
	s_ashr_i32 s3, s2, 31
	s_lshl_b64 s[36:37], s[2:3], 10
	s_nop 3
	v_cvt_pk_bf16_f32 v92, v92, v93
	v_cvt_pk_bf16_f32 v93, v94, v95
	v_lshl_add_u64 v[94:95], v[100:101], 0, s[36:37]
	global_store_dwordx2 v[94:95], v[92:93], off
	s_waitcnt lgkmcnt(10)
	v_mfma_f32_16x16x32_bf16 v[92:95], v[200:203], v[224:227], 0
	ds_read_b64_tr_b16 v[250:251], v147 offset:27968
	ds_read2_b32 v[204:205], v164 offset1:1
	v_mfma_f32_16x16x32_bf16 v[92:95], v[96:99], v[216:219], v[92:95]
	s_waitcnt lgkmcnt(11)
	v_mfma_f32_16x16x32_bf16 v[92:95], v[188:191], v[228:231], v[92:95]
	ds_read2_b32 v[206:207], v165 offset1:1
	s_nop 7
	v_cvt_pk_bf16_f32 v92, v92, v93
	v_cvt_pk_bf16_f32 v93, v94, v95
	v_lshl_add_u64 v[94:95], v[102:103], 0, s[36:37]
	global_store_dwordx2 v[94:95], v[92:93], off
	s_waitcnt lgkmcnt(11)
	v_pk_mul_f32 v[88:89], v[88:89], v[232:233]
	ds_read_b64_tr_b16 v[208:209], v146 offset:28000
	s_waitcnt lgkmcnt(11)
	v_pk_mul_f32 v[90:91], v[90:91], v[234:235]
	ds_read_b64_tr_b16 v[210:211], v147 offset:28000
	s_waitcnt lgkmcnt(9)
	v_mfma_f32_16x16x32_bf16 v[88:91], v[236:239], v[200:203], v[88:91]
	ds_read2_b32 v[212:213], v187 offset1:1
	ds_read2_b32 v[214:215], v186 offset1:1
	s_waitcnt vmcnt(11)
	ds_write_b128 v121, v[48:51] offset:11776
	s_waitcnt vmcnt(10)
	ds_write_b128 v122, v[56:59]
	s_waitcnt lgkmcnt(11)
	v_pk_mul_f32 v[72:73], v[72:73], v[244:245]
	s_waitcnt lgkmcnt(10)
	v_pk_mul_f32 v[74:75], v[74:75], v[246:247]
	s_nop 1
	v_mfma_f32_16x16x32_bf16 v[72:75], v[240:243], v[200:203], v[72:75]
	s_waitcnt lgkmcnt(7)
	v_pk_mul_f32 v[76:77], v[76:77], v[204:205]
	s_waitcnt lgkmcnt(6)
	v_pk_mul_f32 v[78:79], v[78:79], v[206:207]
	s_nop 1
	v_mfma_f32_16x16x32_bf16 v[76:79], v[248:251], v[200:203], v[76:79]
	s_waitcnt lgkmcnt(3)
	v_pk_mul_f32 v[80:81], v[80:81], v[212:213]
	s_waitcnt lgkmcnt(2)
	v_pk_mul_f32 v[82:83], v[82:83], v[214:215]
	s_nop 1
	v_mfma_f32_16x16x32_bf16 v[84:87], v[208:211], v[200:203], v[80:83]
	s_and_saveexec_b64 s[36:37], s[38:39]
	ds_write_b128 v148, v[52:55]
	s_or_b64 exec, exec, s[36:37]
	s_and_saveexec_b64 s[36:37], s[40:41]
	ds_write_b32 v149, v119 offset:19968
	s_or_b64 exec, exec, s[36:37]
	s_cmp_gt_u32 s24, 61
	s_waitcnt lgkmcnt(0)
	s_barrier
	ds_read_b64_tr_b16 v[200:201], v123 offset:11776
	ds_read_b64_tr_b16 v[202:203], v124 offset:11776
	ds_read_b128 v[204:207], v125
	ds_read2_b64 v[208:211], v152 offset0:64 offset1:68
	ds_read2_b64 v[212:215], v152 offset0:72 offset1:76
	ds_read2_b64 v[216:219], v151 offset0:64 offset1:68
	ds_read_b128 v[224:227], v127
	ds_read2_b64 v[228:231], v151 offset0:72 offset1:76
	ds_read2_b32 v[232:233], v153 offset1:1
	ds_read2_b32 v[234:235], v156 offset1:1
	ds_read_b64_tr_b16 v[238:239], v144 offset:7168
	ds_read_b64_tr_b16 v[242:243], v144 offset:7200
	s_cbranch_scc1 .LBB0_630
	v_add_u32_e32 v48, 0x100, v150
	s_movk_i32 s2, 0x100
	v_cmp_gt_i32_e32 vcc, s2, v48
	v_mov_b32_e32 v50, s21
	v_mov_b32_e32 v51, s22
	v_cndmask_b32_e32 v49, v174, v175, vcc
	v_add3_u32 v49, v132, v49, s27
	v_cndmask_b32_e32 v48, v150, v48, vcc
	v_add_u32_e32 v49, 0xfffff661, v49
	v_cndmask_b32_e32 v50, v50, v51, vcc
	v_cndmask_b32_e64 v48, v49, v48, s[0:1]
	v_add_u32_e32 v48, v48, v50
	s_movk_i32 s2, 0x3800
	v_add_co_u32_e32 v56, vcc, 0xa000, v112
	v_mad_i64_i32 v[48:49], s[2:3], v48, s2, v[104:105]
	s_nop 0
	v_addc_co_u32_e32 v57, vcc, 0, v113, vcc
	global_load_dwordx4 v[48:51], v[48:49], off offset:1024
	s_nop 0
	global_load_dwordx4 v[56:59], v[56:57], off nt
	s_and_saveexec_b64 s[36:37], s[38:39]
	s_cbranch_execz .LBB0_627
	v_lshl_add_u64 v[52:53], v[106:107], 0, s[44:45]
	v_add_co_u32_e32 v52, vcc, 0x12841000, v52
	s_nop 1
	v_addc_co_u32_e32 v53, vcc, 0, v53, vcc
	global_load_dwordx4 v[52:55], v[52:53], off nt

; DI void gla_scan_item(const P& p, int seq, unsigned char* smem) {
;     ...
;     auto loadr = [&](GlaRegs& R, int c) {
;         if (c >= 72) return;
;         { const int pos = tid >> 4, ch = tid & 15; R.rv = *(const u32x4*)(S + (size_t)prow(b, dir, 32 * c + pos) * NP + C_GLA_V + 128 * h + 8 * ch); }
;         { const int t2 = tid & 255, pos = t2 >> 3, ch = t2 & 7; const bf16_t* src = (tid < 256 ? QT : KO) + ((size_t)seq * PT + 32 * c + pos) * 64 + 8 * ch; R.rq = __builtin_nontemporal_load((const u32x4*)src); }
;         if (tid < 128) { const int i = tid >> 2, ch = tid & 3; R.ra = __builtin_nontemporal_load((const u32x4*)(AT + (((size_t)seq * 72 + c) * 32 + i) * 32 + 8 * ch)); }
;         if (tid >= 128 && tid < 192) R.rd = DC[((size_t)seq * 72 + c) * 64 + (tid - 128)];
;     };
;     auto storel = [&](const GlaRegs& R, int buf) {
;         unsigned char* base = smem + buf * BUFB;
;         bf16_t* sat = (bf16_t*)base; bf16_t* sqt = (bf16_t*)(base + 2560); bf16_t* sko = (bf16_t*)(base + 2560 + 4608); bf16_t* sv = (bf16_t*)(base + 2560 + 9216); float* sdc = (float*)(base + 2560 + 9216 + 8704);
;         { const int pos = tid >> 4, ch = tid & 15; *(u32x4*)(sv + pos * 136 + 8 * ch) = R.rv; }
;         { const int t2 = tid & 255, pos = t2 >> 3, ch = t2 & 7; *(u32x4*)((tid < 256 ? sqt : sko) + pos * 72 + 8 * ch) = R.rq; }
;         if (tid < 128) { const int i = tid >> 2, ch = tid & 3; *(u32x4*)(sat + i * 40 + 8 * ch) = R.ra; }
;         if (tid >= 128 && tid < 192) sdc[tid - 128] = R.rd;
;     };
;     f32x4 st[4];
; #pragma unroll
;     for (int i = 0; i < 4; ++i) st[i] = (f32x4){0.f, 0.f, 0.f, 0.f};
;     const int sgn = dir ? -1 : 1;
;     auto compute = [&](int c) {
;         const unsigned char* base = smem + (c & 1) * BUFB;
;         const bf16_t* sat = (const bf16_t*)base; const bf16_t* sqt = (const bf16_t*)(base + 2560); const bf16_t* sko = (const bf16_t*)(base + 2560 + 4608); const bf16_t* sv = (const bf16_t*)(base + 2560 + 9216); const float* sdc = (const float*)(base + 2560 + 9216 + 8704);
;         const int dv0 = 16 * w;
;         const bf16x8 vb = tr2(sv + (8 * g + q4) * 136 + dv0 + 4 * p4, sv + (8 * g + 4 + q4) * 136 + dv0 + 4 * p4);
;         bf16x8 bs[2];
;         bs[0] = packacc(st[0], st[1]); bs[1] = packacc(st[2], st[3]);
; #pragma unroll
;         for (int mt = 0; mt < 2; ++mt) {
;             f32x4 acc = (f32x4){0.f, 0.f, 0.f, 0.f};
.LBB0_630:
	v_cvt_pk_bf16_f32 v94, v72, v73
	v_cvt_pk_bf16_f32 v93, v90, v91
	v_cvt_pk_bf16_f32 v92, v88, v89
	v_cvt_pk_bf16_f32 v95, v74, v75
	s_waitcnt lgkmcnt(9)
	v_mfma_f32_16x16x32_bf16 v[80:83], v[200:203], v[204:207], 0
	ds_read_b64_tr_b16 v[236:237], v143 offset:7168
	ds_read_b64_tr_b16 v[240:241], v143 offset:7200
	ds_read2_b32 v[244:245], v158 offset1:1
	s_add_i32 s4, s26, 64
	s_add_i32 s5, s26, 0xffffff40
	s_add_i32 s6, s27, 32
	s_add_i32 s7, s27, 0xfffff820
	s_and_b64 s[2:3], s[0:1], exec
	s_cselect_b32 s2, s4, s7
	s_waitcnt lgkmcnt(11)
	v_mfma_f32_16x16x32_bf16 v[80:83], v[92:95], v[208:211], v[80:83]
	ds_read2_b32 v[246:247], v157 offset1:1
	v_cvt_pk_bf16_f32 v190, v84, v85
	v_cvt_pk_bf16_f32 v189, v78, v79
	v_cvt_pk_bf16_f32 v188, v76, v77
	v_cvt_pk_bf16_f32 v191, v86, v87
	s_add_i32 s4, s2, s22
	s_and_b64 s[2:3], s[0:1], exec
	s_cselect_b32 s2, s5, s6
	s_add_i32 s2, s2, s21
	s_cmp_lt_u32 s24, 4
	s_waitcnt lgkmcnt(11)
	v_mfma_f32_16x16x32_bf16 v[80:83], v[188:191], v[212:215], v[80:83]
	ds_read_b64_tr_b16 v[248:249], v143 offset:7232
	s_cselect_b32 s2, s4, s2
	s_ashr_i32 s3, s2, 31
	s_lshl_b64 s[36:37], s[2:3], 10
	s_nop 3
	v_cvt_pk_bf16_f32 v80, v80, v81
	v_cvt_pk_bf16_f32 v81, v82, v83
	v_lshl_add_u64 v[82:83], v[100:101], 0, s[36:37]
	global_store_dwordx2 v[82:83], v[80:81], off
	s_waitcnt lgkmcnt(10)
	v_mfma_f32_16x16x32_bf16 v[80:83], v[200:203], v[224:227], 0
	ds_read_b64_tr_b16 v[250:251], v144 offset:7232
	ds_read2_b32 v[204:205], v154 offset1:1
	v_mfma_f32_16x16x32_bf16 v[80:83], v[92:95], v[216:219], v[80:83]
	s_waitcnt lgkmcnt(11)
	v_mfma_f32_16x16x32_bf16 v[80:83], v[188:191], v[228:231], v[80:83]
	ds_read2_b32 v[206:207], v155 offset1:1
	s_nop 7
	v_cvt_pk_bf16_f32 v80, v80, v81
	v_cvt_pk_bf16_f32 v81, v82, v83
	v_lshl_add_u64 v[82:83], v[102:103], 0, s[36:37]
	global_store_dwordx2 v[82:83], v[80:81], off
	s_waitcnt lgkmcnt(11)
	v_pk_mul_f32 v[80:81], v[88:89], v[232:233]
	ds_read_b64_tr_b16 v[208:209], v143 offset:7264
	s_waitcnt lgkmcnt(11)
	v_pk_mul_f32 v[82:83], v[90:91], v[234:235]
	ds_read_b64_tr_b16 v[210:211], v144 offset:7264
	s_waitcnt lgkmcnt(9)
	v_mfma_f32_16x16x32_bf16 v[92:95], v[236:239], v[200:203], v[80:83]
	ds_read2_b32 v[212:213], v161 offset1:1
	ds_read2_b32 v[214:215], v160 offset1:1
	s_waitcnt vmcnt(11)
	ds_write_b128 v121, v[60:63] offset:32512
	s_waitcnt vmcnt(10)
	ds_write_b128 v122, v[68:71] offset:20736
	s_nop 2
	s_waitcnt lgkmcnt(11)
	v_pk_mul_f32 v[72:73], v[72:73], v[244:245]
	s_waitcnt lgkmcnt(10)
	v_pk_mul_f32 v[74:75], v[74:75], v[246:247]
	s_nop 1
	v_mfma_f32_16x16x32_bf16 v[72:75], v[240:243], v[200:203], v[72:75]
	s_waitcnt lgkmcnt(7)
	v_pk_mul_f32 v[76:77], v[76:77], v[204:205]
	s_waitcnt lgkmcnt(6)
	v_pk_mul_f32 v[78:79], v[78:79], v[206:207]
	s_nop 1
	v_mfma_f32_16x16x32_bf16 v[80:83], v[248:251], v[200:203], v[76:79]
	s_nop 2
	s_waitcnt lgkmcnt(3)
	v_pk_mul_f32 v[84:85], v[84:85], v[212:213]
	s_waitcnt lgkmcnt(2)
	v_pk_mul_f32 v[86:87], v[86:87], v[214:215]
	s_nop 1
	v_mfma_f32_16x16x32_bf16 v[88:91], v[208:211], v[200:203], v[84:87]
	s_and_saveexec_b64 s[36:37], s[38:39]
	ds_write_b128 v148, v[64:67] offset:20736
	s_or_b64 exec, exec, s[36:37]
	s_and_saveexec_b64 s[36:37], s[40:41]
	ds_write_b32 v149, v120 offset:40704
	s_or_b64 exec, exec, s[36:37]
	s_cmp_gt_u32 s24, 60
	s_waitcnt lgkmcnt(0)
	s_barrier
	s_cbranch_scc1 .LBB0_579
	v_add_u32_e32 v60, 0x120, v150
	s_movk_i32 s2, 0x100
	v_cmp_gt_i32_e32 vcc, s2, v60
	v_add_u32_e32 v61, 32, v150
	v_mov_b32_e32 v63, s22
	v_cndmask_b32_e32 v62, v174, v175, vcc
	v_add3_u32 v62, v132, v62, s27
	v_cndmask_b32_e32 v60, v61, v60, vcc
	v_mov_b32_e32 v61, s21
	v_add_u32_e32 v62, 0xfffff641, v62
	v_cndmask_b32_e32 v61, v61, v63, vcc
	v_cndmask_b32_e64 v60, v62, v60, s[0:1]
	v_add_u32_e32 v60, v60, v61
	s_movk_i32 s2, 0x3800
	v_add_co_u32_e32 v68, vcc, 0xb000, v112
	v_mad_i64_i32 v[60:61], s[2:3], v60, s2, v[104:105]
	s_nop 0
	v_addc_co_u32_e32 v69, vcc, 0, v113, vcc
	global_load_dwordx4 v[60:63], v[60:61], off offset:1024
	s_nop 0
	global_load_dwordx4 v[68:71], v[68:69], off nt
	s_and_saveexec_b64 s[36:37], s[38:39]
	s_cbranch_execz .LBB0_637
	v_lshl_add_u64 v[64:65], v[106:107], 0, s[44:45]
	v_add_co_u32_e32 v64, vcc, 0x12841000, v64
	s_nop 1
	v_addc_co_u32_e32 v65, vcc, 0, v65, vcc
	global_load_dwordx4 v[64:67], v[64:65], off offset:2048 nt
